# step 2 rebalance: CKV GEMM gives 3 tiles to the workgroups that had one CQ tile and 1 tile to those that had two (unit stride 128/512, c = blockIdx)
# baseline (speedup 1.0000x reference)
;     DI bool next(int i, Unit& u) const {
;         const int rd = i / nseg; u.seg = i - rd * nseg;
;         const long L = (long)rd * G + c; if (L >= nwg) return false;
;         int wgid = (int)L; { const int q = nwg / NXCD, r = nwg % NXCD, xcd = wgid % NXCD, off = wgid / NXCD; wgid = (xcd < r ? xcd * (q + 1) : r * (q + 1) + (xcd - r) * q) + off; }
;         const int nig = WGM * nN, gid = wgid / nig, fm = gid * WGM, gsz = (nM - fm) < WGM ? (nM - fm) : WGM;
;         u.pm = fm + ((wgid % nig) % gsz); u.pn = (wgid % nig) / gsz; return true;
; DI void run_gemm(const int tid, unsigned char* shm, const GD& d) {
;     pg8::Gemm g; g.A = d.A; g.Bt = d.Bt; g.M = d.M; g.N = d.N; g.K = d.K; g.lda = d.lda; g.nseg = d.nseg; g.segA = d.segA; g.segB = d.segB;
;     pg8::EpiAny E; E.mode = d.mode; E.O = d.O; E.ldc = d.ldc; E.sigc = d.sigc; E.Z = d.Z;
;     pg8::Order S; S.init(d.M, d.N, d.nseg, (int)gridDim.x, (int)((blockIdx.x + d.coff) % gridDim.x));
.LBB0_606:
	s_waitcnt vmcnt(5)
	v_mov_b32_e32 v20, v193
	s_load_dword s0, s[98:99], 0x10
	s_mul_i32 s20, s85, s10
	v_readfirstlane_b32 s33, v20
	s_waitcnt lgkmcnt(0)
	s_lshr_b32 s0, s0, 16
	s_cmp_lg_u32 s0, 0
	s_cselect_b64 s[0:1], -1, 0
	s_cmp_lg_u64 s[0:1], 0
	s_addc_u32 s5, s3, 0
	v_cvt_f32_u32_e32 v0, s5
	s_sub_i32 s1, 0, s5
	s_add_i32 s0, s12, s2
	v_rcp_iflag_f32_e32 v0, v0
	s_nop 0
	v_mul_f32_e32 v0, 0x4f7ffffe, v0
	v_cvt_u32_f32_e32 v0, v0
	s_nop 0
	v_readfirstlane_b32 s6, v0
	s_mul_i32 s1, s1, s6
	s_mul_hi_u32 s1, s6, s1
	s_add_i32 s6, s6, s1
	s_mul_hi_u32 s1, s0, s6
	s_mul_i32 s1, s1, s5
	s_sub_i32 s0, s0, s1
	s_sub_i32 s1, s0, s5
	s_cmp_ge_u32 s0, s5
	s_cselect_b32 s0, s1, s0
	s_sub_i32 s1, s0, s5
	s_cmp_ge_u32 s0, s5
	s_cselect_b32 s47, s1, s0
	s_add_i32 s0, s82, s81
	s_cmp_lg_u32 s0, 5
	s_cbranch_scc1 .Lckv_bal_done
	s_cmp_lg_u32 s3, 0x100
	s_cbranch_scc1 .Lckv_bal_done
	s_mov_b32 s47, s2
	s_cmp_lt_u32 s2, 0x80
	s_movk_i32 s5, 0x80
	s_movk_i32 s0, 0x200
	s_cselect_b32 s5, s0, s5
.Lckv_bal_done:
	s_cmp_lt_i32 s47, s20
	s_cselect_b64 s[0:1], -1, 0
	s_cmp_ge_i32 s47, s20
	s_cbranch_scc0 .LBB0_608
	s_andn2_b64 vcc, exec, s[0:1]
	s_cbranch_vccnz .LBB0_555
	s_branch .LBB0_613
